# hand-written K and V^T unit epilogue (one base/stride selection per unit, widened stores) plus per-round rotation of the regular workgroups' window positions and kind-0 first units for the K/V-owning
# speedup vs baseline: 1.0019x; 1.0019x over previous
;     __device__ __forceinline__ bool next(int i, Unit& u) const {
;         if (G == 256) {
;             if (i < 24) { const int l = i * 32 + (c >> 3); int pm = l / 6, pn = 6 * (c & 7) + l % 6; pn = (pn % 3) * 16 + pn / 3;
;                 u.pm = pm; u.pn = pn; u.kind = pn >> 4; u.A = U + (size_t)pm * TILE; u.B = Win + (size_t)pn * TILE; return true; }
.LBB0_109:
	s_ashr_i32 s0, s2, 3
	s_cmp_lt_u32 s0, 4
	s_cbranch_scc0 .Lsch0_reg
	s_mul_i32 s0, s0, 3
	s_branch .Lsch0_done
.Lsch0_reg:
	s_sub_i32 s0, s0, 4
	s_cmp_lt_u32 s0, 8
	s_cbranch_scc0 .Lsch0_tail
	s_lshr_b32 s1, s0, 1
	s_and_b32 s0, s0, 1
	s_mul_i32 s1, s1, 3
	s_add_i32 s0, s0, s1
	s_add_i32 s0, s0, 1
	s_branch .Lsch0_done
.Lsch0_tail:
	s_add_i32 s0, s0, 4
.Lsch0_done:
	s_mul_hi_i32 s1, s0, 0x2aaaaaab
	s_lshr_b32 s4, s1, 31
	s_add_i32 s96, s1, s4
	s_and_b32 s1, s2, 7
	s_mul_i32 s4, s96, 6
	s_mul_i32 s1, s1, 6
	s_sub_i32 s0, s0, s4
	s_add_i32 s0, s0, s1
	s_bfe_i32 s1, s0, 0x80000
	s_mulk_i32 s1, 0x56
	s_bfe_u32 s4, s1, 0x1000f
	s_bfe_u32 s1, s1, 0x80008
	s_add_i32 s1, s1, s4
	s_mul_i32 s4, s1, 3
	s_sub_i32 s0, s0, s4
	s_sext_i32_i8 s0, s0
	s_lshl_b32 s0, s0, 4
	s_sext_i32_i8 s1, s1
	s_add_i32 s90, s0, s1
	s_ashr_i32 s97, s96, 31
	s_ashr_i32 s13, s90, 4
	s_lshl_b64 s[0:1], s[96:97], 19
	s_add_u32 s4, s24, s0
	s_addc_u32 s5, s25, s1
	s_ashr_i32 s91, s90, 31
	s_lshl_b64 s[0:1], s[90:91], 19
	s_add_u32 s92, s26, s0
	s_addc_u32 s93, s27, s1
	s_mov_b64 s[0:1], -1

;     __device__ __forceinline__ bool next(int i, Unit& u) const {
;         if (G == 256) {
;             if (i < 24) { const int l = i * 32 + (c >> 3); int pm = l / 6, pn = 6 * (c & 7) + l % 6; pn = (pn % 3) * 16 + pn / 3;
;                 u.pm = pm; u.pn = pn; u.kind = pn >> 4; u.A = U + (size_t)pm * TILE; u.B = Win + (size_t)pn * TILE; return true; }
.Lsch_reg:
	s_sub_i32 s28, s28, 4
	s_lshl_b32 s80, s54, 3
	s_add_i32 s28, s28, s80
	s_mul_i32 s80, s28, 2341
	s_lshr_b32 s80, s80, 16
	s_mul_i32 s80, s80, 28
	s_sub_i32 s28, s28, s80
	s_cmp_lt_u32 s28, s29
	s_cbranch_scc1 .Lsch_same
	s_sub_i32 s28, s28, s29
	s_cmp_lt_u32 s28, 8
	s_cbranch_scc0 .Lsch_tail
	s_add_i32 s12, s12, s29
	s_add_i32 s12, s12, 1
	s_lshr_b32 s29, s28, 1
	s_mul_i32 s29, s29, 3
	s_add_i32 s12, s12, s29
	s_and_b32 s28, s28, 1
	s_add_i32 s12, s12, s28
	s_branch .Lsch_done

; __device__ __forceinline__ u32x2 pk4(f32x4 v) { u32x2 r; r.x = pk_bf16(v[0], v[1]); r.y = pk_bf16(v[2], v[3]); return r; }
;     __device__ __forceinline__ void operator()(const f32x4 (&acc)[2][2][4][2], const Unit& u, int wr, int wc, int fr, int fq) const {
;     ...
;         } else {
;             const int r0 = wr * 64 + fr, c0 = wc * 32 + fq * 4;
; #pragma unroll
;             for (int ai = 0; ai < 2; ++ai)
; #pragma unroll
;                 for (int m = 0; m < 4; ++m)
; #pragma unroll
;                     for (int bj = 0; bj < 2; ++bj)
; #pragma unroll
;                         for (int n = 0; n < 2; ++n) {
;                             const int r = r0 + ai * 128 + m * 16, c = c0 + bj * 128 + n * 16;
;                             if (u.kind == 3) *(u32x2*)(KB + (size_t)(u.pm * 256 + r) * 1024 + u.pn * 256 + c) = pk4(acc[ai][bj][m][n]);
;                             else             *(u32x2*)(VT + ((size_t)u.pn * 1024 + u.pm * 256 + r) * 256 + c) = pk4(acc[ai][bj][m][n]);
;                         }
.LBB0_140:
	s_cmp_eq_u32 s13, 3
	s_cbranch_scc0 .Lkv_vt
	s_lshl_b32 s4, s90, 9
	s_add_u32 s98, s56, s4
	s_addc_u32 s99, s57, 0
	s_lshl_b32 s4, s96, 8
	v_add_u32_e32 v128, s4, v146
	v_lshlrev_b32_e32 v128, 11, v128
	s_mov_b32 s100, 0x8000
	s_mov_b32 s101, 0x28000
	s_branch .Lkv_go
.Lkv_vt:
	s_mov_b64 s[98:99], s[38:39]
	s_lshl_b32 s4, s90, 10
	s_lshl_b32 s5, s96, 8
	s_add_u32 s4, s4, s5
	v_add_u32_e32 v128, s4, v146
	v_lshlrev_b32_e32 v128, 9, v128
	s_mov_b32 s100, 0x2000
	s_mov_b32 s101, 0xa000
.Lkv_go:
	v_lshl_add_u32 v128, v148, 1, v128
	v_mbcnt_lo_u32_b32 v129, -1, 0
	v_mbcnt_hi_u32_b32 v129, -1, v129
	v_lshrrev_b32_e32 v129, 1, v129
	v_and_b32_e32 v129, 24, v129
	v_add_u32_e32 v128, v128, v129
	v_cvt_pk_bf16_f32 v132, v116, v117
	v_cvt_pk_bf16_f32 v133, v118, v119
	v_cvt_pk_bf16_f32 v134, v124, v125
	v_cvt_pk_bf16_f32 v135, v126, v127
	v_cvt_pk_bf16_f32 v136, v120, v121
	v_cvt_pk_bf16_f32 v137, v122, v123
	v_cvt_pk_bf16_f32 v138, v112, v113
	v_cvt_pk_bf16_f32 v139, v114, v115
	s_nop 1
	v_permlane32_swap_b32_e32 v132, v134
	v_permlane32_swap_b32_e32 v133, v135
	v_permlane32_swap_b32_e32 v136, v138
	v_permlane32_swap_b32_e32 v137, v139
	v_permlane16_swap_b32_e32 v132, v134
	v_permlane16_swap_b32_e32 v133, v135
	v_permlane16_swap_b32_e32 v136, v138
	v_permlane16_swap_b32_e32 v137, v139
	global_store_dwordx4 v128, v[132:135], s[98:99]
	global_store_dwordx4 v128, v[136:139], s[98:99] offset:256
	s_add_u32 s98, s98, s100
	s_addc_u32 s99, s99, 0
	s_nop 0
	v_cvt_pk_bf16_f32 v132, v84, v85
	v_cvt_pk_bf16_f32 v133, v86, v87
	v_cvt_pk_bf16_f32 v134, v108, v109
	v_cvt_pk_bf16_f32 v135, v110, v111
	v_cvt_pk_bf16_f32 v136, v104, v105
	v_cvt_pk_bf16_f32 v137, v106, v107
	v_cvt_pk_bf16_f32 v138, v80, v81
	v_cvt_pk_bf16_f32 v139, v82, v83
	s_nop 1
	v_permlane32_swap_b32_e32 v132, v134
	v_permlane32_swap_b32_e32 v133, v135
	v_permlane32_swap_b32_e32 v136, v138
	v_permlane32_swap_b32_e32 v137, v139
	v_permlane16_swap_b32_e32 v132, v134
	v_permlane16_swap_b32_e32 v133, v135
	v_permlane16_swap_b32_e32 v136, v138
	v_permlane16_swap_b32_e32 v137, v139
	global_store_dwordx4 v128, v[132:135], s[98:99]
	global_store_dwordx4 v128, v[136:139], s[98:99] offset:256
	s_add_u32 s98, s98, s100
	s_addc_u32 s99, s99, 0
	s_nop 0
	v_cvt_pk_bf16_f32 v132, v76, v77
	v_cvt_pk_bf16_f32 v133, v78, v79
	v_cvt_pk_bf16_f32 v134, v100, v101
	v_cvt_pk_bf16_f32 v135, v102, v103
	v_cvt_pk_bf16_f32 v136, v96, v97
	v_cvt_pk_bf16_f32 v137, v98, v99
	v_cvt_pk_bf16_f32 v138, v72, v73
	v_cvt_pk_bf16_f32 v139, v74, v75
	s_nop 1
	v_permlane32_swap_b32_e32 v132, v134
	v_permlane32_swap_b32_e32 v133, v135
	v_permlane32_swap_b32_e32 v136, v138
	v_permlane32_swap_b32_e32 v137, v139
	v_permlane16_swap_b32_e32 v132, v134
	v_permlane16_swap_b32_e32 v133, v135
	v_permlane16_swap_b32_e32 v136, v138
	v_permlane16_swap_b32_e32 v137, v139
	global_store_dwordx4 v128, v[132:135], s[98:99]
	global_store_dwordx4 v128, v[136:139], s[98:99] offset:256
	s_add_u32 s98, s98, s100
	s_addc_u32 s99, s99, 0
	s_nop 0
	v_cvt_pk_bf16_f32 v132, v68, v69
	v_cvt_pk_bf16_f32 v133, v70, v71
	v_cvt_pk_bf16_f32 v134, v92, v93
	v_cvt_pk_bf16_f32 v135, v94, v95
	v_cvt_pk_bf16_f32 v136, v88, v89
	v_cvt_pk_bf16_f32 v137, v90, v91
	v_cvt_pk_bf16_f32 v138, v64, v65
	v_cvt_pk_bf16_f32 v139, v66, v67
	s_nop 1
	v_permlane32_swap_b32_e32 v132, v134
	v_permlane32_swap_b32_e32 v133, v135
	v_permlane32_swap_b32_e32 v136, v138
	v_permlane32_swap_b32_e32 v137, v139
	v_permlane16_swap_b32_e32 v132, v134
	v_permlane16_swap_b32_e32 v133, v135
	v_permlane16_swap_b32_e32 v136, v138
	v_permlane16_swap_b32_e32 v137, v139
	global_store_dwordx4 v128, v[132:135], s[98:99]
	global_store_dwordx4 v128, v[136:139], s[98:99] offset:256
	s_add_u32 s98, s98, s101
	s_addc_u32 s99, s99, 0
	s_nop 0
	v_cvt_pk_bf16_f32 v132, v52, v53
	v_cvt_pk_bf16_f32 v133, v54, v55
	v_cvt_pk_bf16_f32 v134, v60, v61
	v_cvt_pk_bf16_f32 v135, v62, v63
	v_cvt_pk_bf16_f32 v136, v56, v57
	v_cvt_pk_bf16_f32 v137, v58, v59
	v_cvt_pk_bf16_f32 v138, v48, v49
	v_cvt_pk_bf16_f32 v139, v50, v51
	s_nop 1
	v_permlane32_swap_b32_e32 v132, v134
	v_permlane32_swap_b32_e32 v133, v135
	v_permlane32_swap_b32_e32 v136, v138
	v_permlane32_swap_b32_e32 v137, v139
	v_permlane16_swap_b32_e32 v132, v134
	v_permlane16_swap_b32_e32 v133, v135
	v_permlane16_swap_b32_e32 v136, v138
	v_permlane16_swap_b32_e32 v137, v139
	global_store_dwordx4 v128, v[132:135], s[98:99]
	global_store_dwordx4 v128, v[136:139], s[98:99] offset:256
	s_add_u32 s98, s98, s100
	s_addc_u32 s99, s99, 0
	s_nop 0
	v_cvt_pk_bf16_f32 v132, v20, v21
	v_cvt_pk_bf16_f32 v133, v22, v23
	v_cvt_pk_bf16_f32 v134, v44, v45
	v_cvt_pk_bf16_f32 v135, v46, v47
	v_cvt_pk_bf16_f32 v136, v40, v41
	v_cvt_pk_bf16_f32 v137, v42, v43
	v_cvt_pk_bf16_f32 v138, v16, v17
	v_cvt_pk_bf16_f32 v139, v18, v19
	s_nop 1
	v_permlane32_swap_b32_e32 v132, v134
	v_permlane32_swap_b32_e32 v133, v135
	v_permlane32_swap_b32_e32 v136, v138
	v_permlane32_swap_b32_e32 v137, v139
	v_permlane16_swap_b32_e32 v132, v134
	v_permlane16_swap_b32_e32 v133, v135
	v_permlane16_swap_b32_e32 v136, v138
	v_permlane16_swap_b32_e32 v137, v139
	global_store_dwordx4 v128, v[132:135], s[98:99]
	global_store_dwordx4 v128, v[136:139], s[98:99] offset:256
	s_add_u32 s98, s98, s100
	s_addc_u32 s99, s99, 0
	s_nop 0
	v_cvt_pk_bf16_f32 v132, v12, v13
	v_cvt_pk_bf16_f32 v133, v14, v15
	v_cvt_pk_bf16_f32 v134, v36, v37
	v_cvt_pk_bf16_f32 v135, v38, v39
	v_cvt_pk_bf16_f32 v136, v32, v33
	v_cvt_pk_bf16_f32 v137, v34, v35
	v_cvt_pk_bf16_f32 v138, v8, v9
	v_cvt_pk_bf16_f32 v139, v10, v11
	s_nop 1
	v_permlane32_swap_b32_e32 v132, v134
	v_permlane32_swap_b32_e32 v133, v135
	v_permlane32_swap_b32_e32 v136, v138
	v_permlane32_swap_b32_e32 v137, v139
	v_permlane16_swap_b32_e32 v132, v134
	v_permlane16_swap_b32_e32 v133, v135
	v_permlane16_swap_b32_e32 v136, v138
	v_permlane16_swap_b32_e32 v137, v139
	global_store_dwordx4 v128, v[132:135], s[98:99]
	global_store_dwordx4 v128, v[136:139], s[98:99] offset:256
	s_add_u32 s98, s98, s100
	s_addc_u32 s99, s99, 0
	s_nop 0
	v_cvt_pk_bf16_f32 v132, v4, v5
	v_cvt_pk_bf16_f32 v133, v6, v7
	v_cvt_pk_bf16_f32 v134, v28, v29
	v_cvt_pk_bf16_f32 v135, v30, v31
	v_cvt_pk_bf16_f32 v136, v24, v25
	v_cvt_pk_bf16_f32 v137, v26, v27
	v_cvt_pk_bf16_f32 v138, v0, v1
	v_cvt_pk_bf16_f32 v139, v2, v3
	s_nop 1
	v_permlane32_swap_b32_e32 v132, v134
	v_permlane32_swap_b32_e32 v133, v135
	v_permlane32_swap_b32_e32 v136, v138
	v_permlane32_swap_b32_e32 v137, v139
	v_permlane16_swap_b32_e32 v132, v134
	v_permlane16_swap_b32_e32 v133, v135
	v_permlane16_swap_b32_e32 v136, v138
	v_permlane16_swap_b32_e32 v137, v139
	global_store_dwordx4 v128, v[132:135], s[98:99]
	global_store_dwordx4 v128, v[136:139], s[98:99] offset:256
	s_nop 0
	s_branch .LBB0_287
